# speedup vs baseline: 1.0126x; 1.0090x over previous
.LBB0_38:
	s_add_u32 s2, s0, 0xffc50080
	s_addc_u32 s3, s1, -1
	s_add_i32 s96, 0, 0x10000
	s_cmp_eq_u32 s57, 12
	s_cselect_b32 s41, s53, s3
	s_cselect_b32 s40, s52, s2
	s_cselect_b32 s3, s22, s56
	s_cselect_b32 s2, s47, s49
	s_add_i32 s97, 0, 0x14000
	v_add_u32_e32 v102, s96, v241
	v_add_u32_e32 v142, s97, v241
	ds_read_b128 v[74:77], v102
	ds_read_b128 v[86:89], v102 offset:1024
	ds_read_b128 v[98:101], v102 offset:2048
	ds_read_b128 v[102:105], v102 offset:3072
	ds_read_b128 v[114:117], v142
	ds_read_b128 v[126:129], v142 offset:1024
	ds_read_b128 v[130:133], v142 offset:2048
	ds_read_b128 v[142:145], v142 offset:3072
	v_lshl_add_u64 v[194:195], s[0:1], 0, v[210:211]
	s_add_i32 m0, s60, 0xc000
	ds_read_b128 v[162:165], v242
	ds_read_b128 v[166:169], v242 offset:1024
	ds_read_b128 v[170:173], v242 offset:2048
	ds_read_b128 v[174:177], v242 offset:3072
	ds_read_b128 v[178:181], v242 offset:4096
	ds_read_b128 v[182:185], v242 offset:5120
	ds_read_b128 v[186:189], v242 offset:6144
	ds_read_b128 v[190:193], v242 offset:7168
	global_load_lds_dwordx4 v[194:195], off
	v_lshl_add_u64 v[194:195], v[194:195], 0, s[72:73]
	s_add_i32 m0, s60, 0xe000
	s_nop 0
	global_load_lds_dwordx4 v[194:195], off
	s_waitcnt vmcnt(8)
	s_waitcnt lgkmcnt(0)
	s_barrier
	s_setprio 1
	v_mfma_f32_16x16x32_bf16 v[158:161], v[74:77], v[162:165], v[158:161]
	v_mfma_f32_16x16x32_bf16 v[158:161], v[86:89], v[166:169], v[158:161]
	v_mfma_f32_16x16x32_bf16 v[154:157], v[102:105], v[166:169], v[154:157]
	v_mfma_f32_16x16x32_bf16 v[154:157], v[98:101], v[162:165], v[154:157]
	v_mfma_f32_16x16x32_bf16 v[134:137], v[98:101], v[170:173], v[134:137]
	v_mfma_f32_16x16x32_bf16 v[134:137], v[102:105], v[174:177], v[134:137]
	v_mfma_f32_16x16x32_bf16 v[138:141], v[86:89], v[174:177], v[138:141]
	v_mfma_f32_16x16x32_bf16 v[138:141], v[74:77], v[170:173], v[138:141]
	v_mfma_f32_16x16x32_bf16 v[110:113], v[74:77], v[178:181], v[110:113]
	v_mfma_f32_16x16x32_bf16 v[110:113], v[86:89], v[182:185], v[110:113]
	v_mfma_f32_16x16x32_bf16 v[106:109], v[102:105], v[182:185], v[106:109]
	v_mfma_f32_16x16x32_bf16 v[106:109], v[98:101], v[178:181], v[106:109]
	v_mfma_f32_16x16x32_bf16 v[78:81], v[98:101], v[186:189], v[78:81]
	v_mfma_f32_16x16x32_bf16 v[78:81], v[102:105], v[190:193], v[78:81]
	v_mfma_f32_16x16x32_bf16 v[82:85], v[86:89], v[190:193], v[82:85]
	v_mfma_f32_16x16x32_bf16 v[82:85], v[74:77], v[186:189], v[82:85]
	v_mfma_f32_16x16x32_bf16 v[66:69], v[130:133], v[186:189], v[66:69]
	v_mfma_f32_16x16x32_bf16 v[66:69], v[142:145], v[190:193], v[66:69]
	v_mfma_f32_16x16x32_bf16 v[146:149], v[142:145], v[166:169], v[146:149]
	v_mfma_f32_16x16x32_bf16 v[146:149], v[130:133], v[162:165], v[146:149]
	v_mfma_f32_16x16x32_bf16 v[150:153], v[114:117], v[162:165], v[150:153]
	v_mfma_f32_16x16x32_bf16 v[150:153], v[126:129], v[166:169], v[150:153]
	v_mfma_f32_16x16x32_bf16 v[122:125], v[126:129], v[174:177], v[122:125]
	v_mfma_f32_16x16x32_bf16 v[122:125], v[114:117], v[170:173], v[122:125]
	v_mfma_f32_16x16x32_bf16 v[118:121], v[130:133], v[170:173], v[118:121]
	v_mfma_f32_16x16x32_bf16 v[118:121], v[142:145], v[174:177], v[118:121]
	v_mfma_f32_16x16x32_bf16 v[90:93], v[142:145], v[182:185], v[90:93]
	v_mfma_f32_16x16x32_bf16 v[90:93], v[130:133], v[178:181], v[90:93]
	v_mfma_f32_16x16x32_bf16 v[94:97], v[114:117], v[178:181], v[94:97]
	v_mfma_f32_16x16x32_bf16 v[94:97], v[126:129], v[182:185], v[94:97]
	v_mfma_f32_16x16x32_bf16 v[70:73], v[126:129], v[190:193], v[70:73]
	v_mfma_f32_16x16x32_bf16 v[70:73], v[114:117], v[186:189], v[70:73]
	s_setprio 0
	s_barrier
	v_lshl_add_u64 v[194:195], s[2:3], 0, v[0:1]
	s_add_i32 s2, s96, s59
	s_mov_b32 m0, s2
	ds_read_b128 v[162:165], v242 offset:16384
	ds_read_b128 v[166:169], v242 offset:17408
	ds_read_b128 v[170:173], v242 offset:18432
	ds_read_b128 v[174:177], v242 offset:19456
	ds_read_b128 v[178:181], v242 offset:20480
	ds_read_b128 v[182:185], v242 offset:21504
	ds_read_b128 v[186:189], v242 offset:22528
	ds_read_b128 v[190:193], v242 offset:23552
	global_load_lds_dwordx4 v[194:195], off
	v_lshl_add_u64 v[196:197], v[194:195], 0, s[10:11]
	s_add_i32 m0, s2, 0x2000
	s_add_i32 s2, s97, s59
	global_load_lds_dwordx4 v[196:197], off
	v_lshl_add_u64 v[196:197], v[194:195], 0, s[26:27]
	s_mov_b32 m0, s2
	s_nop 0
	global_load_lds_dwordx4 v[196:197], off
	v_lshl_add_u64 v[196:197], v[194:195], 0, s[14:15]
	s_add_i32 m0, s2, 0x2000
	s_nop 0
	global_load_lds_dwordx4 v[196:197], off
	v_lshl_add_u64 v[196:197], s[40:41], 0, v[208:209]
	s_mov_b32 m0, s60
	v_lshl_add_u64 v[198:199], v[196:197], 0, s[72:73]
	global_load_lds_dwordx4 v[196:197], off
	s_mov_b32 m0, s61
	s_nop 0
	global_load_lds_dwordx4 v[198:199], off
	s_waitcnt vmcnt(8)
	s_waitcnt lgkmcnt(0)
	s_barrier
	s_setprio 1
	v_mfma_f32_16x16x32_bf16 v[62:65], v[74:77], v[162:165], v[62:65]
	v_mfma_f32_16x16x32_bf16 v[62:65], v[86:89], v[166:169], v[62:65]
	v_mfma_f32_16x16x32_bf16 v[58:61], v[102:105], v[166:169], v[58:61]
	v_mfma_f32_16x16x32_bf16 v[58:61], v[98:101], v[162:165], v[58:61]
	v_mfma_f32_16x16x32_bf16 v[42:45], v[98:101], v[170:173], v[42:45]
	v_mfma_f32_16x16x32_bf16 v[42:45], v[102:105], v[174:177], v[42:45]
	v_mfma_f32_16x16x32_bf16 v[46:49], v[86:89], v[174:177], v[46:49]
	v_mfma_f32_16x16x32_bf16 v[46:49], v[74:77], v[170:173], v[46:49]
	v_mfma_f32_16x16x32_bf16 v[30:33], v[74:77], v[178:181], v[30:33]
	v_mfma_f32_16x16x32_bf16 v[30:33], v[86:89], v[182:185], v[30:33]
	v_mfma_f32_16x16x32_bf16 v[26:29], v[102:105], v[182:185], v[26:29]
	v_mfma_f32_16x16x32_bf16 v[26:29], v[98:101], v[178:181], v[26:29]
	v_mfma_f32_16x16x32_bf16 v[10:13], v[98:101], v[186:189], v[10:13]
	v_mfma_f32_16x16x32_bf16 v[10:13], v[102:105], v[190:193], v[10:13]
	v_mfma_f32_16x16x32_bf16 v[14:17], v[86:89], v[190:193], v[14:17]
	v_mfma_f32_16x16x32_bf16 v[14:17], v[74:77], v[186:189], v[14:17]
	v_mfma_f32_16x16x32_bf16 v[2:5], v[130:133], v[186:189], v[2:5]
	v_mfma_f32_16x16x32_bf16 v[2:5], v[142:145], v[190:193], v[2:5]
	v_mfma_f32_16x16x32_bf16 v[50:53], v[142:145], v[166:169], v[50:53]
	v_mfma_f32_16x16x32_bf16 v[50:53], v[130:133], v[162:165], v[50:53]
	v_mfma_f32_16x16x32_bf16 v[54:57], v[114:117], v[162:165], v[54:57]
	v_mfma_f32_16x16x32_bf16 v[54:57], v[126:129], v[166:169], v[54:57]
	v_mfma_f32_16x16x32_bf16 v[38:41], v[126:129], v[174:177], v[38:41]
	v_mfma_f32_16x16x32_bf16 v[38:41], v[114:117], v[170:173], v[38:41]
	v_mfma_f32_16x16x32_bf16 v[34:37], v[130:133], v[170:173], v[34:37]
	v_mfma_f32_16x16x32_bf16 v[34:37], v[142:145], v[174:177], v[34:37]
	v_mfma_f32_16x16x32_bf16 v[18:21], v[142:145], v[182:185], v[18:21]
	v_mfma_f32_16x16x32_bf16 v[18:21], v[130:133], v[178:181], v[18:21]
	v_mfma_f32_16x16x32_bf16 v[22:25], v[114:117], v[178:181], v[22:25]
	v_mfma_f32_16x16x32_bf16 v[22:25], v[126:129], v[182:185], v[22:25]
	v_mfma_f32_16x16x32_bf16 v[6:9], v[126:129], v[190:193], v[6:9]
	v_mfma_f32_16x16x32_bf16 v[6:9], v[114:117], v[186:189], v[6:9]
	s_setprio 0
	s_barrier
	s_add_i32 s40, 0, 0x18000
	s_add_i32 s41, 0, 0x1c000
	v_add_u32_e32 v102, s40, v241
	v_add_u32_e32 v142, s41, v241
	ds_read_b128 v[74:77], v102
	ds_read_b128 v[86:89], v102 offset:1024
	ds_read_b128 v[98:101], v102 offset:2048
	ds_read_b128 v[102:105], v102 offset:3072
	ds_read_b128 v[114:117], v142
	ds_read_b128 v[126:129], v142 offset:1024
	ds_read_b128 v[130:133], v142 offset:2048
	ds_read_b128 v[142:145], v142 offset:3072
	s_mov_b64 s[2:3], 0x3b0000
	s_mov_b32 m0, s62
	v_lshl_add_u64 v[198:199], v[196:197], 0, s[2:3]
	s_mov_b64 s[2:3], 0x588000
	ds_read_b128 v[162:165], v242 offset:32768
	ds_read_b128 v[166:169], v242 offset:33792
	ds_read_b128 v[170:173], v242 offset:34816
	ds_read_b128 v[174:177], v242 offset:35840
	ds_read_b128 v[178:181], v242 offset:36864
	ds_read_b128 v[182:185], v242 offset:37888
	ds_read_b128 v[186:189], v242 offset:38912
	ds_read_b128 v[190:193], v242 offset:39936
	global_load_lds_dwordx4 v[198:199], off
	v_lshl_add_u64 v[198:199], v[196:197], 0, s[2:3]
	s_mov_b32 m0, s63
	s_nop 0
	global_load_lds_dwordx4 v[198:199], off
	s_waitcnt vmcnt(8)
	s_waitcnt lgkmcnt(0)
	s_barrier
	s_setprio 1
	v_mfma_f32_16x16x32_bf16 v[158:161], v[74:77], v[162:165], v[158:161]
	v_mfma_f32_16x16x32_bf16 v[158:161], v[86:89], v[166:169], v[158:161]
	v_mfma_f32_16x16x32_bf16 v[154:157], v[102:105], v[166:169], v[154:157]
	v_mfma_f32_16x16x32_bf16 v[154:157], v[98:101], v[162:165], v[154:157]
	v_mfma_f32_16x16x32_bf16 v[134:137], v[98:101], v[170:173], v[134:137]
	v_mfma_f32_16x16x32_bf16 v[134:137], v[102:105], v[174:177], v[134:137]
	v_mfma_f32_16x16x32_bf16 v[138:141], v[86:89], v[174:177], v[138:141]
	v_mfma_f32_16x16x32_bf16 v[138:141], v[74:77], v[170:173], v[138:141]
	v_mfma_f32_16x16x32_bf16 v[110:113], v[74:77], v[178:181], v[110:113]
	v_mfma_f32_16x16x32_bf16 v[110:113], v[86:89], v[182:185], v[110:113]
	v_mfma_f32_16x16x32_bf16 v[106:109], v[102:105], v[182:185], v[106:109]
	v_mfma_f32_16x16x32_bf16 v[106:109], v[98:101], v[178:181], v[106:109]
	v_mfma_f32_16x16x32_bf16 v[78:81], v[98:101], v[186:189], v[78:81]
	v_mfma_f32_16x16x32_bf16 v[78:81], v[102:105], v[190:193], v[78:81]
	v_mfma_f32_16x16x32_bf16 v[82:85], v[86:89], v[190:193], v[82:85]
	v_mfma_f32_16x16x32_bf16 v[82:85], v[74:77], v[186:189], v[82:85]
	v_mfma_f32_16x16x32_bf16 v[66:69], v[130:133], v[186:189], v[66:69]
	v_mfma_f32_16x16x32_bf16 v[66:69], v[142:145], v[190:193], v[66:69]
	v_mfma_f32_16x16x32_bf16 v[146:149], v[142:145], v[166:169], v[146:149]
	v_mfma_f32_16x16x32_bf16 v[146:149], v[130:133], v[162:165], v[146:149]
	v_mfma_f32_16x16x32_bf16 v[150:153], v[114:117], v[162:165], v[150:153]
	v_mfma_f32_16x16x32_bf16 v[150:153], v[126:129], v[166:169], v[150:153]
	v_mfma_f32_16x16x32_bf16 v[122:125], v[126:129], v[174:177], v[122:125]
	v_mfma_f32_16x16x32_bf16 v[122:125], v[114:117], v[170:173], v[122:125]
	v_mfma_f32_16x16x32_bf16 v[118:121], v[130:133], v[170:173], v[118:121]
	v_mfma_f32_16x16x32_bf16 v[118:121], v[142:145], v[174:177], v[118:121]
	v_mfma_f32_16x16x32_bf16 v[90:93], v[142:145], v[182:185], v[90:93]
	v_mfma_f32_16x16x32_bf16 v[90:93], v[130:133], v[178:181], v[90:93]
	v_mfma_f32_16x16x32_bf16 v[94:97], v[114:117], v[178:181], v[94:97]
	v_mfma_f32_16x16x32_bf16 v[94:97], v[126:129], v[182:185], v[94:97]
	v_mfma_f32_16x16x32_bf16 v[70:73], v[126:129], v[190:193], v[70:73]
	v_mfma_f32_16x16x32_bf16 v[70:73], v[114:117], v[186:189], v[70:73]
	s_setprio 0
	s_barrier
	s_add_i32 s2, s40, s59
	v_lshl_add_u64 v[198:199], v[194:195], 0, s[30:31]
	s_mov_b32 m0, s2
	ds_read_b128 v[162:165], v242 offset:49152
	ds_read_b128 v[166:169], v242 offset:50176
	ds_read_b128 v[170:173], v242 offset:51200
	ds_read_b128 v[174:177], v242 offset:52224
	ds_read_b128 v[178:181], v242 offset:53248
	ds_read_b128 v[182:185], v242 offset:54272
	ds_read_b128 v[186:189], v242 offset:55296
	ds_read_b128 v[190:193], v242 offset:56320
	global_load_lds_dwordx4 v[198:199], off
	v_lshl_add_u64 v[198:199], v[194:195], 0, s[24:25]
	s_add_i32 m0, s2, 0x2000
	s_add_i32 s2, s41, s59
	global_load_lds_dwordx4 v[198:199], off
	v_lshl_add_u64 v[198:199], v[194:195], 0, s[50:51]
	s_mov_b32 m0, s2
	v_lshl_add_u64 v[194:195], v[194:195], 0, s[4:5]
	global_load_lds_dwordx4 v[198:199], off
	s_add_i32 m0, s2, 0x2000
	s_mov_b64 s[2:3], 0x1d8080
	global_load_lds_dwordx4 v[194:195], off
	v_lshl_add_u64 v[194:195], v[196:197], 0, s[30:31]
	s_mov_b32 m0, s66
	s_nop 0
	global_load_lds_dwordx4 v[194:195], off
	v_lshl_add_u64 v[194:195], v[196:197], 0, s[2:3]
	s_mov_b32 m0, s67
	s_nop 0
	global_load_lds_dwordx4 v[194:195], off
	s_waitcnt vmcnt(8)
	s_waitcnt lgkmcnt(0)
	s_barrier
	s_setprio 1
	v_mfma_f32_16x16x32_bf16 v[62:65], v[74:77], v[162:165], v[62:65]
	v_mfma_f32_16x16x32_bf16 v[62:65], v[86:89], v[166:169], v[62:65]
	v_mfma_f32_16x16x32_bf16 v[58:61], v[102:105], v[166:169], v[58:61]
	v_mfma_f32_16x16x32_bf16 v[58:61], v[98:101], v[162:165], v[58:61]
	v_mfma_f32_16x16x32_bf16 v[42:45], v[98:101], v[170:173], v[42:45]
	v_mfma_f32_16x16x32_bf16 v[42:45], v[102:105], v[174:177], v[42:45]
	v_mfma_f32_16x16x32_bf16 v[46:49], v[86:89], v[174:177], v[46:49]
	v_mfma_f32_16x16x32_bf16 v[46:49], v[74:77], v[170:173], v[46:49]
	v_mfma_f32_16x16x32_bf16 v[30:33], v[74:77], v[178:181], v[30:33]
	v_mfma_f32_16x16x32_bf16 v[30:33], v[86:89], v[182:185], v[30:33]
	v_mfma_f32_16x16x32_bf16 v[26:29], v[102:105], v[182:185], v[26:29]
	v_mfma_f32_16x16x32_bf16 v[26:29], v[98:101], v[178:181], v[26:29]
	v_mfma_f32_16x16x32_bf16 v[10:13], v[98:101], v[186:189], v[10:13]
	v_mfma_f32_16x16x32_bf16 v[10:13], v[102:105], v[190:193], v[10:13]
	v_mfma_f32_16x16x32_bf16 v[14:17], v[86:89], v[190:193], v[14:17]
	v_mfma_f32_16x16x32_bf16 v[14:17], v[74:77], v[186:189], v[14:17]
	v_mfma_f32_16x16x32_bf16 v[2:5], v[130:133], v[186:189], v[2:5]
	v_mfma_f32_16x16x32_bf16 v[2:5], v[142:145], v[190:193], v[2:5]
	v_mfma_f32_16x16x32_bf16 v[50:53], v[142:145], v[166:169], v[50:53]
	v_mfma_f32_16x16x32_bf16 v[50:53], v[130:133], v[162:165], v[50:53]
	v_mfma_f32_16x16x32_bf16 v[54:57], v[114:117], v[162:165], v[54:57]
	v_mfma_f32_16x16x32_bf16 v[54:57], v[126:129], v[166:169], v[54:57]
	v_mfma_f32_16x16x32_bf16 v[38:41], v[126:129], v[174:177], v[38:41]
	v_mfma_f32_16x16x32_bf16 v[38:41], v[114:117], v[170:173], v[38:41]
	v_mfma_f32_16x16x32_bf16 v[34:37], v[130:133], v[170:173], v[34:37]
	v_mfma_f32_16x16x32_bf16 v[34:37], v[142:145], v[174:177], v[34:37]
	v_mfma_f32_16x16x32_bf16 v[18:21], v[142:145], v[182:185], v[18:21]
	v_mfma_f32_16x16x32_bf16 v[18:21], v[130:133], v[178:181], v[18:21]
	v_mfma_f32_16x16x32_bf16 v[22:25], v[114:117], v[178:181], v[22:25]
	v_mfma_f32_16x16x32_bf16 v[22:25], v[126:129], v[182:185], v[22:25]
	v_mfma_f32_16x16x32_bf16 v[6:9], v[126:129], v[190:193], v[6:9]
	v_mfma_f32_16x16x32_bf16 v[6:9], v[114:117], v[186:189], v[6:9]
	s_setprio 0
	s_barrier
	s_add_i32 s57, s57, 2
	s_add_u32 s0, s0, 0x100
	s_addc_u32 s1, s1, 0
	s_add_u32 s49, s49, 0x100
	s_addc_u32 s56, s56, 0
	s_cmp_gt_u32 s57, 13
	s_cbranch_scc0 .LBB0_38
	s_and_b64 vcc, exec, s[44:45]
	s_cbranch_vccz .LBB0_41
	s_barrier

.LBB0_406:
	s_add_u32 s2, s58, 0xfff80080
	s_addc_u32 s3, s59, -1
	s_add_i32 s67, 0, 0x10000
	s_cmp_eq_u32 s66, 28
	s_cselect_b32 s61, s53, s3
	s_cselect_b32 s60, s62, s2
	s_cselect_b32 s3, s49, s65
	s_cselect_b32 s2, s63, s64
	s_add_i32 vcc_lo, 0, 0x14000
	v_add_u32_e32 v142, s67, v224
	v_add_u32_e32 v158, vcc_lo, v224
	ds_read_b128 v[126:129], v142
	ds_read_b128 v[134:137], v142 offset:1024
	ds_read_b128 v[138:141], v142 offset:2048
	ds_read_b128 v[142:145], v142 offset:3072
	ds_read_b128 v[146:149], v158
	ds_read_b128 v[150:153], v158 offset:1024
	ds_read_b128 v[154:157], v158 offset:2048
	ds_read_b128 v[158:161], v158 offset:3072
	v_lshl_add_u64 v[196:197], s[58:59], 0, v[190:191]
	s_add_i32 m0, s95, 0xc000
	ds_read_b128 v[162:165], v225
	ds_read_b128 v[166:169], v225 offset:1024
	ds_read_b128 v[170:173], v225 offset:2048
	ds_read_b128 v[174:177], v225 offset:3072
	ds_read_b128 v[178:181], v225 offset:4096
	ds_read_b128 v[182:185], v225 offset:5120
	ds_read_b128 v[186:189], v225 offset:6144
	ds_read_b128 v[192:195], v225 offset:7168
	global_load_lds_dwordx4 v[196:197], off
	v_lshl_add_u64 v[196:197], v[196:197], 0, s[26:27]
	s_add_i32 m0, s95, 0xe000
	s_nop 0
	global_load_lds_dwordx4 v[196:197], off
	s_waitcnt vmcnt(8)
	s_waitcnt lgkmcnt(0)
	s_barrier
	s_setprio 1
	v_mfma_f32_16x16x32_bf16 v[130:133], v[126:129], v[162:165], v[130:133]
	v_mfma_f32_16x16x32_bf16 v[130:133], v[134:137], v[166:169], v[130:133]
	v_mfma_f32_16x16x32_bf16 v[122:125], v[142:145], v[166:169], v[122:125]
	v_mfma_f32_16x16x32_bf16 v[122:125], v[138:141], v[162:165], v[122:125]
	v_mfma_f32_16x16x32_bf16 v[106:109], v[138:141], v[170:173], v[106:109]
	v_mfma_f32_16x16x32_bf16 v[106:109], v[142:145], v[174:177], v[106:109]
	v_mfma_f32_16x16x32_bf16 v[110:113], v[134:137], v[174:177], v[110:113]
	v_mfma_f32_16x16x32_bf16 v[110:113], v[126:129], v[170:173], v[110:113]
	v_mfma_f32_16x16x32_bf16 v[94:97], v[126:129], v[178:181], v[94:97]
	v_mfma_f32_16x16x32_bf16 v[94:97], v[134:137], v[182:185], v[94:97]
	v_mfma_f32_16x16x32_bf16 v[90:93], v[142:145], v[182:185], v[90:93]
	v_mfma_f32_16x16x32_bf16 v[90:93], v[138:141], v[178:181], v[90:93]
	v_mfma_f32_16x16x32_bf16 v[74:77], v[138:141], v[186:189], v[74:77]
	v_mfma_f32_16x16x32_bf16 v[74:77], v[142:145], v[192:195], v[74:77]
	v_mfma_f32_16x16x32_bf16 v[78:81], v[134:137], v[192:195], v[78:81]
	v_mfma_f32_16x16x32_bf16 v[78:81], v[126:129], v[186:189], v[78:81]
	v_mfma_f32_16x16x32_bf16 v[66:69], v[154:157], v[186:189], v[66:69]
	v_mfma_f32_16x16x32_bf16 v[66:69], v[158:161], v[192:195], v[66:69]
	v_mfma_f32_16x16x32_bf16 v[114:117], v[158:161], v[166:169], v[114:117]
	v_mfma_f32_16x16x32_bf16 v[114:117], v[154:157], v[162:165], v[114:117]
	v_mfma_f32_16x16x32_bf16 v[118:121], v[146:149], v[162:165], v[118:121]
	v_mfma_f32_16x16x32_bf16 v[118:121], v[150:153], v[166:169], v[118:121]
	v_mfma_f32_16x16x32_bf16 v[102:105], v[150:153], v[174:177], v[102:105]
	v_mfma_f32_16x16x32_bf16 v[102:105], v[146:149], v[170:173], v[102:105]
	v_mfma_f32_16x16x32_bf16 v[98:101], v[154:157], v[170:173], v[98:101]
	v_mfma_f32_16x16x32_bf16 v[98:101], v[158:161], v[174:177], v[98:101]
	v_mfma_f32_16x16x32_bf16 v[82:85], v[158:161], v[182:185], v[82:85]
	v_mfma_f32_16x16x32_bf16 v[82:85], v[154:157], v[178:181], v[82:85]
	v_mfma_f32_16x16x32_bf16 v[86:89], v[146:149], v[178:181], v[86:89]
	v_mfma_f32_16x16x32_bf16 v[86:89], v[150:153], v[182:185], v[86:89]
	v_mfma_f32_16x16x32_bf16 v[70:73], v[150:153], v[192:195], v[70:73]
	v_mfma_f32_16x16x32_bf16 v[70:73], v[146:149], v[186:189], v[70:73]
	s_setprio 0
	s_barrier
	v_lshl_add_u64 v[196:197], s[2:3], 0, v[0:1]
	s_add_i32 s2, s67, s94
	s_mov_b32 m0, s2
	ds_read_b128 v[162:165], v225 offset:16384
	ds_read_b128 v[166:169], v225 offset:17408
	ds_read_b128 v[170:173], v225 offset:18432
	ds_read_b128 v[174:177], v225 offset:19456
	ds_read_b128 v[178:181], v225 offset:20480
	ds_read_b128 v[182:185], v225 offset:21504
	ds_read_b128 v[186:189], v225 offset:22528
	ds_read_b128 v[192:195], v225 offset:23552
	global_load_lds_dwordx4 v[196:197], off
	v_lshl_add_u64 v[198:199], v[196:197], 0, s[26:27]
	s_add_i32 m0, s2, 0x2000
	s_add_i32 s2, vcc_lo, s94
	global_load_lds_dwordx4 v[198:199], off
	v_lshl_add_u64 v[198:199], v[196:197], 0, s[20:21]
	s_mov_b32 m0, s2
	s_nop 0
	global_load_lds_dwordx4 v[198:199], off
	v_lshl_add_u64 v[198:199], v[196:197], 0, s[6:7]
	s_add_i32 m0, s2, 0x2000
	s_nop 0
	global_load_lds_dwordx4 v[198:199], off
	v_lshl_add_u64 v[198:199], s[60:61], 0, v[0:1]
	s_mov_b32 m0, s95
	v_lshl_add_u64 v[200:201], v[198:199], 0, s[26:27]
	global_load_lds_dwordx4 v[198:199], off
	s_mov_b32 m0, s42
	s_nop 0
	global_load_lds_dwordx4 v[200:201], off
	s_waitcnt vmcnt(8)
	s_waitcnt lgkmcnt(0)
	s_barrier
	s_setprio 1
	v_mfma_f32_16x16x32_bf16 v[62:65], v[126:129], v[162:165], v[62:65]
	v_mfma_f32_16x16x32_bf16 v[62:65], v[134:137], v[166:169], v[62:65]
	v_mfma_f32_16x16x32_bf16 v[58:61], v[142:145], v[166:169], v[58:61]
	v_mfma_f32_16x16x32_bf16 v[58:61], v[138:141], v[162:165], v[58:61]
	v_mfma_f32_16x16x32_bf16 v[42:45], v[138:141], v[170:173], v[42:45]
	v_mfma_f32_16x16x32_bf16 v[42:45], v[142:145], v[174:177], v[42:45]
	v_mfma_f32_16x16x32_bf16 v[46:49], v[134:137], v[174:177], v[46:49]
	v_mfma_f32_16x16x32_bf16 v[46:49], v[126:129], v[170:173], v[46:49]
	v_mfma_f32_16x16x32_bf16 v[30:33], v[126:129], v[178:181], v[30:33]
	v_mfma_f32_16x16x32_bf16 v[30:33], v[134:137], v[182:185], v[30:33]
	v_mfma_f32_16x16x32_bf16 v[26:29], v[142:145], v[182:185], v[26:29]
	v_mfma_f32_16x16x32_bf16 v[26:29], v[138:141], v[178:181], v[26:29]
	v_mfma_f32_16x16x32_bf16 v[10:13], v[138:141], v[186:189], v[10:13]
	v_mfma_f32_16x16x32_bf16 v[10:13], v[142:145], v[192:195], v[10:13]
	v_mfma_f32_16x16x32_bf16 v[14:17], v[134:137], v[192:195], v[14:17]
	v_mfma_f32_16x16x32_bf16 v[14:17], v[126:129], v[186:189], v[14:17]
	v_mfma_f32_16x16x32_bf16 v[2:5], v[154:157], v[186:189], v[2:5]
	v_mfma_f32_16x16x32_bf16 v[2:5], v[158:161], v[192:195], v[2:5]
	v_mfma_f32_16x16x32_bf16 v[50:53], v[158:161], v[166:169], v[50:53]
	v_mfma_f32_16x16x32_bf16 v[50:53], v[154:157], v[162:165], v[50:53]
	v_mfma_f32_16x16x32_bf16 v[54:57], v[146:149], v[162:165], v[54:57]
	v_mfma_f32_16x16x32_bf16 v[54:57], v[150:153], v[166:169], v[54:57]
	v_mfma_f32_16x16x32_bf16 v[38:41], v[150:153], v[174:177], v[38:41]
	v_mfma_f32_16x16x32_bf16 v[38:41], v[146:149], v[170:173], v[38:41]
	v_mfma_f32_16x16x32_bf16 v[34:37], v[154:157], v[170:173], v[34:37]
	v_mfma_f32_16x16x32_bf16 v[34:37], v[158:161], v[174:177], v[34:37]
	v_mfma_f32_16x16x32_bf16 v[18:21], v[158:161], v[182:185], v[18:21]
	v_mfma_f32_16x16x32_bf16 v[18:21], v[154:157], v[178:181], v[18:21]
	v_mfma_f32_16x16x32_bf16 v[22:25], v[146:149], v[178:181], v[22:25]
	v_mfma_f32_16x16x32_bf16 v[22:25], v[150:153], v[182:185], v[22:25]
	v_mfma_f32_16x16x32_bf16 v[6:9], v[150:153], v[192:195], v[6:9]
	v_mfma_f32_16x16x32_bf16 v[6:9], v[146:149], v[186:189], v[6:9]
	s_setprio 0
	s_barrier
	s_add_i32 s2, 0, 0x18000
	s_add_i32 s3, 0, 0x1c000
	v_add_u32_e32 v142, s2, v224
	v_add_u32_e32 v158, s3, v224
	ds_read_b128 v[126:129], v142
	ds_read_b128 v[134:137], v142 offset:1024
	ds_read_b128 v[138:141], v142 offset:2048
	ds_read_b128 v[142:145], v142 offset:3072
	ds_read_b128 v[146:149], v158
	ds_read_b128 v[150:153], v158 offset:1024
	ds_read_b128 v[154:157], v158 offset:2048
	ds_read_b128 v[158:161], v158 offset:3072
	s_mov_b32 m0, s43
	v_lshl_add_u64 v[200:201], v[198:199], 0, s[20:21]
	ds_read_b128 v[162:165], v225 offset:32768
	ds_read_b128 v[166:169], v225 offset:33792
	ds_read_b128 v[170:173], v225 offset:34816
	ds_read_b128 v[174:177], v225 offset:35840
	ds_read_b128 v[178:181], v225 offset:36864
	ds_read_b128 v[182:185], v225 offset:37888
	ds_read_b128 v[186:189], v225 offset:38912
	ds_read_b128 v[192:195], v225 offset:39936
	global_load_lds_dwordx4 v[200:201], off
	v_lshl_add_u64 v[200:201], v[198:199], 0, s[6:7]
	s_mov_b32 m0, s0
	s_nop 0
	global_load_lds_dwordx4 v[200:201], off
	s_waitcnt vmcnt(8)
	s_waitcnt lgkmcnt(0)
	s_barrier
	s_setprio 1
	v_mfma_f32_16x16x32_bf16 v[130:133], v[126:129], v[162:165], v[130:133]
	v_mfma_f32_16x16x32_bf16 v[130:133], v[134:137], v[166:169], v[130:133]
	v_mfma_f32_16x16x32_bf16 v[122:125], v[142:145], v[166:169], v[122:125]
	v_mfma_f32_16x16x32_bf16 v[122:125], v[138:141], v[162:165], v[122:125]
	v_mfma_f32_16x16x32_bf16 v[106:109], v[138:141], v[170:173], v[106:109]
	v_mfma_f32_16x16x32_bf16 v[106:109], v[142:145], v[174:177], v[106:109]
	v_mfma_f32_16x16x32_bf16 v[110:113], v[134:137], v[174:177], v[110:113]
	v_mfma_f32_16x16x32_bf16 v[110:113], v[126:129], v[170:173], v[110:113]
	v_mfma_f32_16x16x32_bf16 v[94:97], v[126:129], v[178:181], v[94:97]
	v_mfma_f32_16x16x32_bf16 v[94:97], v[134:137], v[182:185], v[94:97]
	v_mfma_f32_16x16x32_bf16 v[90:93], v[142:145], v[182:185], v[90:93]
	v_mfma_f32_16x16x32_bf16 v[90:93], v[138:141], v[178:181], v[90:93]
	v_mfma_f32_16x16x32_bf16 v[74:77], v[138:141], v[186:189], v[74:77]
	v_mfma_f32_16x16x32_bf16 v[74:77], v[142:145], v[192:195], v[74:77]
	v_mfma_f32_16x16x32_bf16 v[78:81], v[134:137], v[192:195], v[78:81]
	v_mfma_f32_16x16x32_bf16 v[78:81], v[126:129], v[186:189], v[78:81]
	v_mfma_f32_16x16x32_bf16 v[66:69], v[154:157], v[186:189], v[66:69]
	v_mfma_f32_16x16x32_bf16 v[66:69], v[158:161], v[192:195], v[66:69]
	v_mfma_f32_16x16x32_bf16 v[114:117], v[158:161], v[166:169], v[114:117]
	v_mfma_f32_16x16x32_bf16 v[114:117], v[154:157], v[162:165], v[114:117]
	v_mfma_f32_16x16x32_bf16 v[118:121], v[146:149], v[162:165], v[118:121]
	v_mfma_f32_16x16x32_bf16 v[118:121], v[150:153], v[166:169], v[118:121]
	v_mfma_f32_16x16x32_bf16 v[102:105], v[150:153], v[174:177], v[102:105]
	v_mfma_f32_16x16x32_bf16 v[102:105], v[146:149], v[170:173], v[102:105]
	v_mfma_f32_16x16x32_bf16 v[98:101], v[154:157], v[170:173], v[98:101]
	v_mfma_f32_16x16x32_bf16 v[98:101], v[158:161], v[174:177], v[98:101]
	v_mfma_f32_16x16x32_bf16 v[82:85], v[158:161], v[182:185], v[82:85]
	v_mfma_f32_16x16x32_bf16 v[82:85], v[154:157], v[178:181], v[82:85]
	v_mfma_f32_16x16x32_bf16 v[86:89], v[146:149], v[178:181], v[86:89]
	v_mfma_f32_16x16x32_bf16 v[86:89], v[150:153], v[182:185], v[86:89]
	v_mfma_f32_16x16x32_bf16 v[70:73], v[150:153], v[192:195], v[70:73]
	v_mfma_f32_16x16x32_bf16 v[70:73], v[146:149], v[186:189], v[70:73]
	s_setprio 0
	s_barrier
	s_add_i32 s2, s2, s94
	v_lshl_add_u64 v[200:201], v[196:197], 0, s[30:31]
	s_mov_b32 m0, s2
	ds_read_b128 v[162:165], v225 offset:49152
	ds_read_b128 v[166:169], v225 offset:50176
	ds_read_b128 v[170:173], v225 offset:51200
	ds_read_b128 v[174:177], v225 offset:52224
	ds_read_b128 v[178:181], v225 offset:53248
	ds_read_b128 v[182:185], v225 offset:54272
	ds_read_b128 v[186:189], v225 offset:55296
	ds_read_b128 v[192:195], v225 offset:56320
	global_load_lds_dwordx4 v[200:201], off
	v_lshl_add_u64 v[200:201], v[196:197], 0, s[50:51]
	s_add_i32 m0, s2, 0x2000
	s_add_i32 s2, s3, s94
	global_load_lds_dwordx4 v[200:201], off
	v_lshl_add_u64 v[200:201], v[196:197], 0, s[36:37]
	s_mov_b32 m0, s2
	v_lshl_add_u64 v[196:197], v[196:197], 0, s[88:89]
	global_load_lds_dwordx4 v[200:201], off
	s_add_i32 m0, s2, 0x2000
	s_nop 0
	global_load_lds_dwordx4 v[196:197], off
	v_lshl_add_u64 v[196:197], v[198:199], 0, s[30:31]
	s_mov_b32 m0, s41
	s_nop 0
	global_load_lds_dwordx4 v[196:197], off
	v_lshl_add_u64 v[196:197], v[198:199], 0, s[50:51]
	s_mov_b32 m0, s96
	s_nop 0
	global_load_lds_dwordx4 v[196:197], off
	s_waitcnt vmcnt(8)
	s_waitcnt lgkmcnt(0)
	s_barrier
	s_setprio 1
	v_mfma_f32_16x16x32_bf16 v[62:65], v[126:129], v[162:165], v[62:65]
	v_mfma_f32_16x16x32_bf16 v[62:65], v[134:137], v[166:169], v[62:65]
	v_mfma_f32_16x16x32_bf16 v[58:61], v[142:145], v[166:169], v[58:61]
	v_mfma_f32_16x16x32_bf16 v[58:61], v[138:141], v[162:165], v[58:61]
	v_mfma_f32_16x16x32_bf16 v[42:45], v[138:141], v[170:173], v[42:45]
	v_mfma_f32_16x16x32_bf16 v[42:45], v[142:145], v[174:177], v[42:45]
	v_mfma_f32_16x16x32_bf16 v[46:49], v[134:137], v[174:177], v[46:49]
	v_mfma_f32_16x16x32_bf16 v[46:49], v[126:129], v[170:173], v[46:49]
	v_mfma_f32_16x16x32_bf16 v[30:33], v[126:129], v[178:181], v[30:33]
	v_mfma_f32_16x16x32_bf16 v[30:33], v[134:137], v[182:185], v[30:33]
	v_mfma_f32_16x16x32_bf16 v[26:29], v[142:145], v[182:185], v[26:29]
	v_mfma_f32_16x16x32_bf16 v[26:29], v[138:141], v[178:181], v[26:29]
	v_mfma_f32_16x16x32_bf16 v[10:13], v[138:141], v[186:189], v[10:13]
	v_mfma_f32_16x16x32_bf16 v[10:13], v[142:145], v[192:195], v[10:13]
	v_mfma_f32_16x16x32_bf16 v[14:17], v[134:137], v[192:195], v[14:17]
	v_mfma_f32_16x16x32_bf16 v[14:17], v[126:129], v[186:189], v[14:17]
	v_mfma_f32_16x16x32_bf16 v[2:5], v[154:157], v[186:189], v[2:5]
	v_mfma_f32_16x16x32_bf16 v[2:5], v[158:161], v[192:195], v[2:5]
	v_mfma_f32_16x16x32_bf16 v[50:53], v[158:161], v[166:169], v[50:53]
	v_mfma_f32_16x16x32_bf16 v[50:53], v[154:157], v[162:165], v[50:53]
	v_mfma_f32_16x16x32_bf16 v[54:57], v[146:149], v[162:165], v[54:57]
	v_mfma_f32_16x16x32_bf16 v[54:57], v[150:153], v[166:169], v[54:57]
	v_mfma_f32_16x16x32_bf16 v[38:41], v[150:153], v[174:177], v[38:41]
	v_mfma_f32_16x16x32_bf16 v[38:41], v[146:149], v[170:173], v[38:41]
	v_mfma_f32_16x16x32_bf16 v[34:37], v[154:157], v[170:173], v[34:37]
	v_mfma_f32_16x16x32_bf16 v[34:37], v[158:161], v[174:177], v[34:37]
	v_mfma_f32_16x16x32_bf16 v[18:21], v[158:161], v[182:185], v[18:21]
	v_mfma_f32_16x16x32_bf16 v[18:21], v[154:157], v[178:181], v[18:21]
	v_mfma_f32_16x16x32_bf16 v[22:25], v[146:149], v[178:181], v[22:25]
	v_mfma_f32_16x16x32_bf16 v[22:25], v[150:153], v[182:185], v[22:25]
	v_mfma_f32_16x16x32_bf16 v[6:9], v[150:153], v[192:195], v[6:9]
	v_mfma_f32_16x16x32_bf16 v[6:9], v[146:149], v[186:189], v[6:9]
	s_setprio 0
	s_barrier
	s_add_i32 s66, s66, 2
	s_add_u32 s58, s58, 0x100
	s_addc_u32 s59, s59, 0
	s_add_u32 s64, s64, 0x100
	s_addc_u32 s65, s65, 0
	s_cmp_gt_u32 s66, 29
	s_cbranch_scc0 .LBB0_406
	s_and_b64 vcc, exec, s[44:45]
	s_cbranch_vccz .LBB0_409
	s_barrier

.LBB0_447:
	s_add_u32 s2, s52, 0xfff80080
	s_addc_u32 s3, s53, -1
	s_add_i32 s96, 0, 0x10000
	s_cmp_eq_u32 s95, 28
	s_cselect_b32 s55, s45, s3
	s_cselect_b32 s54, s67, s2
	s_cselect_b32 s3, s43, s94
	s_cselect_b32 s2, s90, s91
	s_add_i32 s97, 0, 0x14000
	v_add_u32_e32 v146, s96, v152
	v_add_u32_e32 v150, s97, v152
	ds_read_b128 v[134:137], v146
	ds_read_b128 v[138:141], v146 offset:1024
	ds_read_b128 v[142:145], v146 offset:2048
	ds_read_b128 v[146:149], v146 offset:3072
	ds_read_b128 v[154:157], v150
	ds_read_b128 v[158:161], v150 offset:1024
	ds_read_b128 v[162:165], v150 offset:2048
	ds_read_b128 v[166:169], v150 offset:3072
	v_lshl_add_u64 v[150:151], s[52:53], 0, v[132:133]
	s_add_i32 m0, s58, 0xc000
	ds_read_b128 v[170:173], v153
	ds_read_b128 v[174:177], v153 offset:1024
	ds_read_b128 v[178:181], v153 offset:2048
	ds_read_b128 v[182:185], v153 offset:3072
	ds_read_b128 v[186:189], v153 offset:4096
	ds_read_b128 v[190:193], v153 offset:5120
	ds_read_b128 v[206:209], v153 offset:6144
	ds_read_b128 v[210:213], v153 offset:7168
	global_load_lds_dwordx4 v[150:151], off
	v_lshl_add_u64 v[150:151], v[150:151], 0, s[26:27]
	s_add_i32 m0, s58, 0xe000
	s_nop 0
	global_load_lds_dwordx4 v[150:151], off
	s_waitcnt vmcnt(8)
	s_waitcnt lgkmcnt(0)
	s_barrier
	s_setprio 1
	v_mfma_f32_16x16x32_bf16 v[126:129], v[134:137], v[170:173], v[126:129]
	v_mfma_f32_16x16x32_bf16 v[126:129], v[138:141], v[174:177], v[126:129]
	v_mfma_f32_16x16x32_bf16 v[122:125], v[146:149], v[174:177], v[122:125]
	v_mfma_f32_16x16x32_bf16 v[122:125], v[142:145], v[170:173], v[122:125]
	v_mfma_f32_16x16x32_bf16 v[106:109], v[142:145], v[178:181], v[106:109]
	v_mfma_f32_16x16x32_bf16 v[106:109], v[146:149], v[182:185], v[106:109]
	v_mfma_f32_16x16x32_bf16 v[110:113], v[138:141], v[182:185], v[110:113]
	v_mfma_f32_16x16x32_bf16 v[110:113], v[134:137], v[178:181], v[110:113]
	v_mfma_f32_16x16x32_bf16 v[94:97], v[134:137], v[186:189], v[94:97]
	v_mfma_f32_16x16x32_bf16 v[94:97], v[138:141], v[190:193], v[94:97]
	v_mfma_f32_16x16x32_bf16 v[90:93], v[146:149], v[190:193], v[90:93]
	v_mfma_f32_16x16x32_bf16 v[90:93], v[142:145], v[186:189], v[90:93]
	v_mfma_f32_16x16x32_bf16 v[74:77], v[142:145], v[206:209], v[74:77]
	v_mfma_f32_16x16x32_bf16 v[74:77], v[146:149], v[210:213], v[74:77]
	v_mfma_f32_16x16x32_bf16 v[78:81], v[138:141], v[210:213], v[78:81]
	v_mfma_f32_16x16x32_bf16 v[78:81], v[134:137], v[206:209], v[78:81]
	v_mfma_f32_16x16x32_bf16 v[66:69], v[162:165], v[206:209], v[66:69]
	v_mfma_f32_16x16x32_bf16 v[66:69], v[166:169], v[210:213], v[66:69]
	v_mfma_f32_16x16x32_bf16 v[114:117], v[166:169], v[174:177], v[114:117]
	v_mfma_f32_16x16x32_bf16 v[114:117], v[162:165], v[170:173], v[114:117]
	v_mfma_f32_16x16x32_bf16 v[118:121], v[154:157], v[170:173], v[118:121]
	v_mfma_f32_16x16x32_bf16 v[118:121], v[158:161], v[174:177], v[118:121]
	v_mfma_f32_16x16x32_bf16 v[102:105], v[158:161], v[182:185], v[102:105]
	v_mfma_f32_16x16x32_bf16 v[102:105], v[154:157], v[178:181], v[102:105]
	v_mfma_f32_16x16x32_bf16 v[98:101], v[162:165], v[178:181], v[98:101]
	v_mfma_f32_16x16x32_bf16 v[98:101], v[166:169], v[182:185], v[98:101]
	v_mfma_f32_16x16x32_bf16 v[82:85], v[166:169], v[190:193], v[82:85]
	v_mfma_f32_16x16x32_bf16 v[82:85], v[162:165], v[186:189], v[82:85]
	v_mfma_f32_16x16x32_bf16 v[86:89], v[154:157], v[186:189], v[86:89]
	v_mfma_f32_16x16x32_bf16 v[86:89], v[158:161], v[190:193], v[86:89]
	v_mfma_f32_16x16x32_bf16 v[70:73], v[158:161], v[210:213], v[70:73]
	v_mfma_f32_16x16x32_bf16 v[70:73], v[154:157], v[206:209], v[70:73]
	s_setprio 0
	s_barrier
	v_lshl_add_u64 v[150:151], s[2:3], 0, v[0:1]
	s_add_i32 s2, s96, s57
	s_mov_b32 m0, s2
	ds_read_b128 v[170:173], v153 offset:16384
	ds_read_b128 v[174:177], v153 offset:17408
	ds_read_b128 v[178:181], v153 offset:18432
	ds_read_b128 v[182:185], v153 offset:19456
	ds_read_b128 v[186:189], v153 offset:20480
	ds_read_b128 v[190:193], v153 offset:21504
	ds_read_b128 v[206:209], v153 offset:22528
	ds_read_b128 v[210:213], v153 offset:23552
	global_load_lds_dwordx4 v[150:151], off
	v_lshl_add_u64 v[194:195], v[150:151], 0, s[26:27]
	s_add_i32 m0, s2, 0x2000
	s_add_i32 s2, s97, s57
	global_load_lds_dwordx4 v[194:195], off
	v_lshl_add_u64 v[194:195], v[150:151], 0, s[20:21]
	s_mov_b32 m0, s2
	s_nop 0
	global_load_lds_dwordx4 v[194:195], off
	v_lshl_add_u64 v[194:195], v[150:151], 0, s[6:7]
	s_add_i32 m0, s2, 0x2000
	s_nop 0
	global_load_lds_dwordx4 v[194:195], off
	v_lshl_add_u64 v[194:195], s[54:55], 0, v[130:131]
	s_mov_b32 m0, s58
	v_lshl_add_u64 v[196:197], v[194:195], 0, s[26:27]
	global_load_lds_dwordx4 v[194:195], off
	s_mov_b32 m0, s59
	s_nop 0
	global_load_lds_dwordx4 v[196:197], off
	s_waitcnt vmcnt(8)
	s_waitcnt lgkmcnt(0)
	s_barrier
	s_setprio 1
	v_mfma_f32_16x16x32_bf16 v[62:65], v[134:137], v[170:173], v[62:65]
	v_mfma_f32_16x16x32_bf16 v[62:65], v[138:141], v[174:177], v[62:65]
	v_mfma_f32_16x16x32_bf16 v[58:61], v[146:149], v[174:177], v[58:61]
	v_mfma_f32_16x16x32_bf16 v[58:61], v[142:145], v[170:173], v[58:61]
	v_mfma_f32_16x16x32_bf16 v[42:45], v[142:145], v[178:181], v[42:45]
	v_mfma_f32_16x16x32_bf16 v[42:45], v[146:149], v[182:185], v[42:45]
	v_mfma_f32_16x16x32_bf16 v[46:49], v[138:141], v[182:185], v[46:49]
	v_mfma_f32_16x16x32_bf16 v[46:49], v[134:137], v[178:181], v[46:49]
	v_mfma_f32_16x16x32_bf16 v[30:33], v[134:137], v[186:189], v[30:33]
	v_mfma_f32_16x16x32_bf16 v[30:33], v[138:141], v[190:193], v[30:33]
	v_mfma_f32_16x16x32_bf16 v[26:29], v[146:149], v[190:193], v[26:29]
	v_mfma_f32_16x16x32_bf16 v[26:29], v[142:145], v[186:189], v[26:29]
	v_mfma_f32_16x16x32_bf16 v[10:13], v[142:145], v[206:209], v[10:13]
	v_mfma_f32_16x16x32_bf16 v[10:13], v[146:149], v[210:213], v[10:13]
	v_mfma_f32_16x16x32_bf16 v[14:17], v[138:141], v[210:213], v[14:17]
	v_mfma_f32_16x16x32_bf16 v[14:17], v[134:137], v[206:209], v[14:17]
	v_mfma_f32_16x16x32_bf16 v[2:5], v[162:165], v[206:209], v[2:5]
	v_mfma_f32_16x16x32_bf16 v[2:5], v[166:169], v[210:213], v[2:5]
	v_mfma_f32_16x16x32_bf16 v[50:53], v[166:169], v[174:177], v[50:53]
	v_mfma_f32_16x16x32_bf16 v[50:53], v[162:165], v[170:173], v[50:53]
	v_mfma_f32_16x16x32_bf16 v[54:57], v[154:157], v[170:173], v[54:57]
	v_mfma_f32_16x16x32_bf16 v[54:57], v[158:161], v[174:177], v[54:57]
	v_mfma_f32_16x16x32_bf16 v[38:41], v[158:161], v[182:185], v[38:41]
	v_mfma_f32_16x16x32_bf16 v[38:41], v[154:157], v[178:181], v[38:41]
	v_mfma_f32_16x16x32_bf16 v[34:37], v[162:165], v[178:181], v[34:37]
	v_mfma_f32_16x16x32_bf16 v[34:37], v[166:169], v[182:185], v[34:37]
	v_mfma_f32_16x16x32_bf16 v[18:21], v[166:169], v[190:193], v[18:21]
	v_mfma_f32_16x16x32_bf16 v[18:21], v[162:165], v[186:189], v[18:21]
	v_mfma_f32_16x16x32_bf16 v[22:25], v[154:157], v[186:189], v[22:25]
	v_mfma_f32_16x16x32_bf16 v[22:25], v[158:161], v[190:193], v[22:25]
	v_mfma_f32_16x16x32_bf16 v[6:9], v[158:161], v[210:213], v[6:9]
	v_mfma_f32_16x16x32_bf16 v[6:9], v[154:157], v[206:209], v[6:9]
	s_setprio 0
	s_barrier
	s_add_i32 s2, 0, 0x18000
	s_add_i32 s3, 0, 0x1c000
	v_add_u32_e32 v146, s2, v152
	v_add_u32_e32 v166, s3, v152
	ds_read_b128 v[134:137], v146
	ds_read_b128 v[138:141], v146 offset:1024
	ds_read_b128 v[142:145], v146 offset:2048
	ds_read_b128 v[146:149], v146 offset:3072
	ds_read_b128 v[154:157], v166
	ds_read_b128 v[158:161], v166 offset:1024
	ds_read_b128 v[162:165], v166 offset:2048
	ds_read_b128 v[166:169], v166 offset:3072
	s_mov_b32 m0, s60
	v_lshl_add_u64 v[196:197], v[194:195], 0, s[20:21]
	ds_read_b128 v[170:173], v153 offset:32768
	ds_read_b128 v[174:177], v153 offset:33792
	ds_read_b128 v[178:181], v153 offset:34816
	ds_read_b128 v[182:185], v153 offset:35840
	ds_read_b128 v[186:189], v153 offset:36864
	ds_read_b128 v[190:193], v153 offset:37888
	ds_read_b128 v[206:209], v153 offset:38912
	ds_read_b128 v[210:213], v153 offset:39936
	global_load_lds_dwordx4 v[196:197], off
	v_lshl_add_u64 v[196:197], v[194:195], 0, s[6:7]
	s_mov_b32 m0, s61
	s_nop 0
	global_load_lds_dwordx4 v[196:197], off
	s_waitcnt vmcnt(8)
	s_waitcnt lgkmcnt(0)
	s_barrier
	s_setprio 1
	v_mfma_f32_16x16x32_bf16 v[126:129], v[134:137], v[170:173], v[126:129]
	v_mfma_f32_16x16x32_bf16 v[126:129], v[138:141], v[174:177], v[126:129]
	v_mfma_f32_16x16x32_bf16 v[122:125], v[146:149], v[174:177], v[122:125]
	v_mfma_f32_16x16x32_bf16 v[122:125], v[142:145], v[170:173], v[122:125]
	v_mfma_f32_16x16x32_bf16 v[106:109], v[142:145], v[178:181], v[106:109]
	v_mfma_f32_16x16x32_bf16 v[106:109], v[146:149], v[182:185], v[106:109]
	v_mfma_f32_16x16x32_bf16 v[110:113], v[138:141], v[182:185], v[110:113]
	v_mfma_f32_16x16x32_bf16 v[110:113], v[134:137], v[178:181], v[110:113]
	v_mfma_f32_16x16x32_bf16 v[94:97], v[134:137], v[186:189], v[94:97]
	v_mfma_f32_16x16x32_bf16 v[94:97], v[138:141], v[190:193], v[94:97]
	v_mfma_f32_16x16x32_bf16 v[90:93], v[146:149], v[190:193], v[90:93]
	v_mfma_f32_16x16x32_bf16 v[90:93], v[142:145], v[186:189], v[90:93]
	v_mfma_f32_16x16x32_bf16 v[74:77], v[142:145], v[206:209], v[74:77]
	v_mfma_f32_16x16x32_bf16 v[74:77], v[146:149], v[210:213], v[74:77]
	v_mfma_f32_16x16x32_bf16 v[78:81], v[138:141], v[210:213], v[78:81]
	v_mfma_f32_16x16x32_bf16 v[78:81], v[134:137], v[206:209], v[78:81]
	v_mfma_f32_16x16x32_bf16 v[66:69], v[162:165], v[206:209], v[66:69]
	v_mfma_f32_16x16x32_bf16 v[66:69], v[166:169], v[210:213], v[66:69]
	v_mfma_f32_16x16x32_bf16 v[114:117], v[166:169], v[174:177], v[114:117]
	v_mfma_f32_16x16x32_bf16 v[114:117], v[162:165], v[170:173], v[114:117]
	v_mfma_f32_16x16x32_bf16 v[118:121], v[154:157], v[170:173], v[118:121]
	v_mfma_f32_16x16x32_bf16 v[118:121], v[158:161], v[174:177], v[118:121]
	v_mfma_f32_16x16x32_bf16 v[102:105], v[158:161], v[182:185], v[102:105]
	v_mfma_f32_16x16x32_bf16 v[102:105], v[154:157], v[178:181], v[102:105]
	v_mfma_f32_16x16x32_bf16 v[98:101], v[162:165], v[178:181], v[98:101]
	v_mfma_f32_16x16x32_bf16 v[98:101], v[166:169], v[182:185], v[98:101]
	v_mfma_f32_16x16x32_bf16 v[82:85], v[166:169], v[190:193], v[82:85]
	v_mfma_f32_16x16x32_bf16 v[82:85], v[162:165], v[186:189], v[82:85]
	v_mfma_f32_16x16x32_bf16 v[86:89], v[154:157], v[186:189], v[86:89]
	v_mfma_f32_16x16x32_bf16 v[86:89], v[158:161], v[190:193], v[86:89]
	v_mfma_f32_16x16x32_bf16 v[70:73], v[158:161], v[210:213], v[70:73]
	v_mfma_f32_16x16x32_bf16 v[70:73], v[154:157], v[206:209], v[70:73]
	s_setprio 0
	s_barrier
	s_add_i32 s2, s2, s57
	v_lshl_add_u64 v[196:197], v[150:151], 0, s[30:31]
	s_mov_b32 m0, s2
	ds_read_b128 v[170:173], v153 offset:49152
	ds_read_b128 v[174:177], v153 offset:50176
	ds_read_b128 v[178:181], v153 offset:51200
	ds_read_b128 v[182:185], v153 offset:52224
	ds_read_b128 v[186:189], v153 offset:53248
	ds_read_b128 v[190:193], v153 offset:54272
	ds_read_b128 v[206:209], v153 offset:55296
	ds_read_b128 v[210:213], v153 offset:56320
	global_load_lds_dwordx4 v[196:197], off
	v_lshl_add_u64 v[196:197], v[150:151], 0, s[50:51]
	s_add_i32 m0, s2, 0x2000
	s_add_i32 s2, s3, s57
	global_load_lds_dwordx4 v[196:197], off
	v_lshl_add_u64 v[196:197], v[150:151], 0, s[36:37]
	s_mov_b32 m0, s2
	v_lshl_add_u64 v[150:151], v[150:151], 0, s[88:89]
	global_load_lds_dwordx4 v[196:197], off
	s_add_i32 m0, s2, 0x2000
	s_nop 0
	global_load_lds_dwordx4 v[150:151], off
	v_lshl_add_u64 v[150:151], v[194:195], 0, s[30:31]
	s_mov_b32 m0, s62
	s_nop 0
	global_load_lds_dwordx4 v[150:151], off
	v_lshl_add_u64 v[150:151], v[194:195], 0, s[50:51]
	s_mov_b32 m0, s63
	s_nop 0
	global_load_lds_dwordx4 v[150:151], off
	s_waitcnt vmcnt(8)
	s_waitcnt lgkmcnt(0)
	s_barrier
	s_setprio 1
	v_mfma_f32_16x16x32_bf16 v[62:65], v[134:137], v[170:173], v[62:65]
	v_mfma_f32_16x16x32_bf16 v[62:65], v[138:141], v[174:177], v[62:65]
	v_mfma_f32_16x16x32_bf16 v[58:61], v[146:149], v[174:177], v[58:61]
	v_mfma_f32_16x16x32_bf16 v[58:61], v[142:145], v[170:173], v[58:61]
	v_mfma_f32_16x16x32_bf16 v[42:45], v[142:145], v[178:181], v[42:45]
	v_mfma_f32_16x16x32_bf16 v[42:45], v[146:149], v[182:185], v[42:45]
	v_mfma_f32_16x16x32_bf16 v[46:49], v[138:141], v[182:185], v[46:49]
	v_mfma_f32_16x16x32_bf16 v[46:49], v[134:137], v[178:181], v[46:49]
	v_mfma_f32_16x16x32_bf16 v[30:33], v[134:137], v[186:189], v[30:33]
	v_mfma_f32_16x16x32_bf16 v[30:33], v[138:141], v[190:193], v[30:33]
	v_mfma_f32_16x16x32_bf16 v[26:29], v[146:149], v[190:193], v[26:29]
	v_mfma_f32_16x16x32_bf16 v[26:29], v[142:145], v[186:189], v[26:29]
	v_mfma_f32_16x16x32_bf16 v[10:13], v[142:145], v[206:209], v[10:13]
	v_mfma_f32_16x16x32_bf16 v[10:13], v[146:149], v[210:213], v[10:13]
	v_mfma_f32_16x16x32_bf16 v[14:17], v[138:141], v[210:213], v[14:17]
	v_mfma_f32_16x16x32_bf16 v[14:17], v[134:137], v[206:209], v[14:17]
	v_mfma_f32_16x16x32_bf16 v[2:5], v[162:165], v[206:209], v[2:5]
	v_mfma_f32_16x16x32_bf16 v[2:5], v[166:169], v[210:213], v[2:5]
	v_mfma_f32_16x16x32_bf16 v[50:53], v[166:169], v[174:177], v[50:53]
	v_mfma_f32_16x16x32_bf16 v[50:53], v[162:165], v[170:173], v[50:53]
	v_mfma_f32_16x16x32_bf16 v[54:57], v[154:157], v[170:173], v[54:57]
	v_mfma_f32_16x16x32_bf16 v[54:57], v[158:161], v[174:177], v[54:57]
	v_mfma_f32_16x16x32_bf16 v[38:41], v[158:161], v[182:185], v[38:41]
	v_mfma_f32_16x16x32_bf16 v[38:41], v[154:157], v[178:181], v[38:41]
	v_mfma_f32_16x16x32_bf16 v[34:37], v[162:165], v[178:181], v[34:37]
	v_mfma_f32_16x16x32_bf16 v[34:37], v[166:169], v[182:185], v[34:37]
	v_mfma_f32_16x16x32_bf16 v[18:21], v[166:169], v[190:193], v[18:21]
	v_mfma_f32_16x16x32_bf16 v[18:21], v[162:165], v[186:189], v[18:21]
	v_mfma_f32_16x16x32_bf16 v[22:25], v[154:157], v[186:189], v[22:25]
	v_mfma_f32_16x16x32_bf16 v[22:25], v[158:161], v[190:193], v[22:25]
	v_mfma_f32_16x16x32_bf16 v[6:9], v[158:161], v[210:213], v[6:9]
	v_mfma_f32_16x16x32_bf16 v[6:9], v[154:157], v[206:209], v[6:9]
	s_setprio 0
	s_barrier
	s_add_i32 s95, s95, 2
	s_add_u32 s52, s52, 0x100
	s_addc_u32 s53, s53, 0
	s_add_u32 s91, s91, 0x100
	s_addc_u32 s94, s94, 0
	s_cmp_gt_u32 s95, 29
	s_cbranch_scc0 .LBB0_447
	s_and_b64 vcc, exec, s[40:41]
	s_cbranch_vccz .LBB0_450
	s_barrier
